# P4 uq/ukv epilogues: 8 row sum-of-squares loads issued at the epilogue head, per-row vmcnt(0) waits behind the row stores removed (on top of P3/P7/P8/P2/P9/P10/P11 epilogue de-serialisation)
# baseline (speedup 1.0000x reference)
; DI unsigned pk2(float lo, float hi) { typedef float v2f __attribute__((ext_vector_type(2))); typedef __bf16 v2b __attribute__((ext_vector_type(2))); v2f v = {lo, hi}; v2b b = __builtin_convertvector(v, v2b); return __builtin_bit_cast(unsigned, b); }
; template <int NP> DI float row_rstd(const float* P, int row, float invn) {
;     if (NP == 0) return 1.0f;
;     return __builtin_amdgcn_rsqf(P[row] * invn + EPS);
; }
;     DI void operator()(const f32x4 (&acc)[2][2][4][2], const Unit& u, int wr, int wc, int fr, int fq) const {
;         const int row0 = u.pm * 256 + wr * 64 + fr, cw = u.pn * 256 + wc * 32 + 8 * fq;
; #pragma unroll
;         for (int ai = 0; ai < 2; ++ai)
; #pragma unroll
;             for (int m = 0; m < 4; ++m) {
;                 const int row = row0 + ai * 128 + m * 16; const float rs = row_rstd<1>(P, row, 1.0f / 384.0f);
; #pragma unroll
;                 for (int bj = 0; bj < 2; ++bj) {
;                     const f32x4 a = acc[ai][bj][m][0] * rs, b = acc[ai][bj][m][1] * rs;
;                     u32x4 w; w.x = pk2(a[0], a[1]); w.y = pk2(a[2], a[3]); w.z = pk2(b[0], b[1]); w.w = pk2(b[2], b[3]);
;                     *(u32x4*)(O + (size_t)row * 768 + cw + bj * 128) = w;
;                 }
.LBB0_1205:
	v_lshl_add_u32 v148, s68, 8, v161
	v_ashrrev_i32_e32 v149, 31, v148
	v_lshl_add_u64 v[152:153], v[148:149], 2, s[18:19]
	global_load_dword v198, v[152:153], off
	global_load_dword v199, v[152:153], off offset:64
	global_load_dword v200, v[152:153], off offset:128
	global_load_dword v201, v[152:153], off offset:192
	global_load_dword v202, v[152:153], off offset:512
	global_load_dword v203, v[152:153], off offset:576
	global_load_dword v204, v[152:153], off offset:640
	global_load_dword v205, v[152:153], off offset:704
	v_lshl_or_b32 v154, s69, 8, v170
	v_mov_b64_e32 v[150:151], s[20:21]
	v_ashrrev_i32_e32 v155, 31, v154
	v_mad_i64_i32 v[176:177], s[42:43], v148, s61, v[150:151]
	v_or_b32_e32 v178, 16, v148
	v_lshlrev_b64 v[154:155], 1, v[154:155]
	v_ashrrev_i32_e32 v179, 31, v178
	v_lshl_add_u64 v[176:177], v[176:177], 0, v[154:155]
	v_lshl_add_u64 v[182:183], v[178:179], 2, s[18:19]
	s_and_b64 vcc, exec, s[2:3]
	s_waitcnt vmcnt(0) lgkmcnt(0)
	v_fmamk_f32 v149, v198, 0x3b2aaaab, v174
	v_rsq_f32_e32 v180, v149
	s_nop 0
	v_pk_mul_f32 v[122:123], v[122:123], v[180:181] op_sel_hi:[1,0]
	v_pk_mul_f32 v[120:121], v[120:121], v[180:181] op_sel_hi:[1,0]
	v_pk_mul_f32 v[126:127], v[126:127], v[180:181] op_sel_hi:[1,0]
	v_pk_mul_f32 v[124:125], v[124:125], v[180:181] op_sel_hi:[1,0]
	v_pk_mul_f32 v[118:119], v[118:119], v[180:181] op_sel_hi:[1,0]
	v_pk_mul_f32 v[116:117], v[116:117], v[180:181] op_sel_hi:[1,0]
	v_pk_mul_f32 v[184:185], v[114:115], v[180:181] op_sel_hi:[1,0]
	v_pk_mul_f32 v[180:181], v[112:113], v[180:181] op_sel_hi:[1,0]
	v_cvt_pk_bf16_f32 v112, v120, v121
	v_cvt_pk_bf16_f32 v113, v122, v123
	v_cvt_pk_bf16_f32 v114, v124, v125
	v_cvt_pk_bf16_f32 v115, v126, v127
	v_cvt_pk_bf16_f32 v116, v116, v117
	v_cvt_pk_bf16_f32 v117, v118, v119
	v_cvt_pk_bf16_f32 v118, v180, v181
	v_cvt_pk_bf16_f32 v119, v184, v185
	flat_store_dwordx4 v[176:177], v[112:115]
	flat_store_dwordx4 v[176:177], v[116:119] offset:256
	s_nop 0
	v_or_b32_e32 v112, 32, v148
	v_mad_i64_i32 v[114:115], s[42:43], v178, s61, v[150:151]
	v_lshl_add_u64 v[114:115], v[114:115], 0, v[154:155]
	s_waitcnt lgkmcnt(0)
	v_fmamk_f32 v113, v199, 0x3b2aaaab, v174
	v_rsq_f32_e32 v116, v113
	v_ashrrev_i32_e32 v113, 31, v112
	v_lshl_add_u64 v[118:119], v[112:113], 2, s[18:19]
	v_pk_mul_f32 v[110:111], v[110:111], v[116:117] op_sel_hi:[1,0]
	v_pk_mul_f32 v[108:109], v[108:109], v[116:117] op_sel_hi:[1,0]
	v_pk_mul_f32 v[106:107], v[106:107], v[116:117] op_sel_hi:[1,0]
	v_pk_mul_f32 v[104:105], v[104:105], v[116:117] op_sel_hi:[1,0]
	v_pk_mul_f32 v[102:103], v[102:103], v[116:117] op_sel_hi:[1,0]
	v_pk_mul_f32 v[100:101], v[100:101], v[116:117] op_sel_hi:[1,0]
	v_pk_mul_f32 v[120:121], v[98:99], v[116:117] op_sel_hi:[1,0]
	v_pk_mul_f32 v[116:117], v[96:97], v[116:117] op_sel_hi:[1,0]
	v_cvt_pk_bf16_f32 v96, v108, v109
	v_cvt_pk_bf16_f32 v97, v110, v111
	v_cvt_pk_bf16_f32 v98, v104, v105
	v_cvt_pk_bf16_f32 v99, v106, v107
	v_cvt_pk_bf16_f32 v100, v100, v101
	v_cvt_pk_bf16_f32 v101, v102, v103
	v_cvt_pk_bf16_f32 v102, v116, v117
	v_cvt_pk_bf16_f32 v103, v120, v121
	flat_store_dwordx4 v[114:115], v[96:99]
	flat_store_dwordx4 v[114:115], v[100:103] offset:256
	s_nop 0
	v_or_b32_e32 v96, 48, v148
	v_mad_i64_i32 v[98:99], s[42:43], v112, s61, v[150:151]
	v_lshl_add_u64 v[98:99], v[98:99], 0, v[154:155]
	s_waitcnt lgkmcnt(0)
	v_fmamk_f32 v97, v200, 0x3b2aaaab, v174
	v_rsq_f32_e32 v100, v97
	v_ashrrev_i32_e32 v97, 31, v96
	v_lshl_add_u64 v[102:103], v[96:97], 2, s[18:19]
	v_pk_mul_f32 v[94:95], v[94:95], v[100:101] op_sel_hi:[1,0]
	v_pk_mul_f32 v[92:93], v[92:93], v[100:101] op_sel_hi:[1,0]
	v_pk_mul_f32 v[90:91], v[90:91], v[100:101] op_sel_hi:[1,0]
	v_pk_mul_f32 v[88:89], v[88:89], v[100:101] op_sel_hi:[1,0]
	v_pk_mul_f32 v[86:87], v[86:87], v[100:101] op_sel_hi:[1,0]
	v_pk_mul_f32 v[84:85], v[84:85], v[100:101] op_sel_hi:[1,0]
	v_pk_mul_f32 v[104:105], v[82:83], v[100:101] op_sel_hi:[1,0]
	v_pk_mul_f32 v[100:101], v[80:81], v[100:101] op_sel_hi:[1,0]
	v_cvt_pk_bf16_f32 v80, v92, v93
	v_cvt_pk_bf16_f32 v81, v94, v95
	v_cvt_pk_bf16_f32 v82, v88, v89
	v_cvt_pk_bf16_f32 v83, v90, v91
	v_cvt_pk_bf16_f32 v84, v84, v85
	v_cvt_pk_bf16_f32 v85, v86, v87
	v_cvt_pk_bf16_f32 v86, v100, v101
	v_cvt_pk_bf16_f32 v87, v104, v105
	flat_store_dwordx4 v[98:99], v[80:83]
	flat_store_dwordx4 v[98:99], v[84:87] offset:256
	s_nop 0
	v_mad_i64_i32 v[82:83], s[42:43], v96, s61, v[150:151]
	v_lshl_add_u64 v[82:83], v[82:83], 0, v[154:155]
	s_waitcnt lgkmcnt(0)
; #define PG8_BAR __builtin_amdgcn_s_barrier()
; DI unsigned pk2(float lo, float hi) { typedef float v2f __attribute__((ext_vector_type(2))); typedef __bf16 v2b __attribute__((ext_vector_type(2))); v2f v = {lo, hi}; v2b b = __builtin_convertvector(v, v2b); return __builtin_bit_cast(unsigned, b); }
; template <class Epi, class Sched, bool ALIGN_EPI = false, bool SP2 = false>
; __device__ __forceinline__ void gemm_phase(PG8_LAS unsigned char* lds, const Gemm g, const Sched& S, const Epi& E) {
;     ...
;         cur = nxt; cA = nA; cB = nB; ++ui;
;         if constexpr (ALIGN_EPI) { if (wr == 1) PG8_BAR; }
;     DI void operator()(const f32x4 (&acc)[2][2][4][2], const Unit& u, int wr, int wc, int fr, int fq) const {
;     ...
;         for (int ai = 0; ai < 2; ++ai)
; #pragma unroll
;             for (int m = 0; m < 4; ++m) {
;                 const int row = row0 + ai * 128 + m * 16; const float rs = row_rstd<1>(P, row, 1.0f / 384.0f);
; #pragma unroll
;                 for (int bj = 0; bj < 2; ++bj) {
;                     const f32x4 a = acc[ai][bj][m][0] * rs, b = acc[ai][bj][m][1] * rs;
;                     u32x4 w; w.x = pk2(a[0], a[1]); w.y = pk2(a[2], a[3]); w.z = pk2(b[0], b[1]); w.w = pk2(b[2], b[3]);
;                     *(u32x4*)(O + (size_t)row * 768 + cw + bj * 128) = w;
;                 }
	v_fmamk_f32 v80, v201, 0x3b2aaaab, v174
	v_rsq_f32_e32 v80, v80
	s_nop 0
	v_pk_mul_f32 v[78:79], v[78:79], v[80:81] op_sel_hi:[1,0]
	v_pk_mul_f32 v[76:77], v[76:77], v[80:81] op_sel_hi:[1,0]
	v_pk_mul_f32 v[74:75], v[74:75], v[80:81] op_sel_hi:[1,0]
	v_pk_mul_f32 v[72:73], v[72:73], v[80:81] op_sel_hi:[1,0]
	v_pk_mul_f32 v[70:71], v[70:71], v[80:81] op_sel_hi:[1,0]
	v_pk_mul_f32 v[68:69], v[68:69], v[80:81] op_sel_hi:[1,0]
	v_pk_mul_f32 v[84:85], v[66:67], v[80:81] op_sel_hi:[1,0]
	v_pk_mul_f32 v[80:81], v[64:65], v[80:81] op_sel_hi:[1,0]
	v_cvt_pk_bf16_f32 v64, v76, v77
	v_cvt_pk_bf16_f32 v65, v78, v79
	v_cvt_pk_bf16_f32 v66, v72, v73
	v_cvt_pk_bf16_f32 v67, v74, v75
	v_cvt_pk_bf16_f32 v68, v68, v69
	v_cvt_pk_bf16_f32 v69, v70, v71
	v_cvt_pk_bf16_f32 v70, v80, v81
	v_cvt_pk_bf16_f32 v71, v84, v85
	flat_store_dwordx4 v[82:83], v[64:67]
	flat_store_dwordx4 v[82:83], v[68:71] offset:256
	s_nop 0
	v_add_u32_e32 v65, 0x80, v148
	v_mad_i64_i32 v[66:67], s[42:43], v65, s61, v[150:151]
	v_lshl_add_u64 v[66:67], v[66:67], 0, v[154:155]
	s_waitcnt lgkmcnt(0)
	v_fmamk_f32 v64, v202, 0x3b2aaaab, v174
	v_rsq_f32_e32 v64, v64
	s_nop 0
	v_pk_mul_f32 v[62:63], v[62:63], v[64:65] op_sel_hi:[1,0]
	v_pk_mul_f32 v[60:61], v[60:61], v[64:65] op_sel_hi:[1,0]
	v_pk_mul_f32 v[58:59], v[58:59], v[64:65] op_sel_hi:[1,0]
	v_pk_mul_f32 v[56:57], v[56:57], v[64:65] op_sel_hi:[1,0]
	v_pk_mul_f32 v[54:55], v[54:55], v[64:65] op_sel_hi:[1,0]
	v_pk_mul_f32 v[52:53], v[52:53], v[64:65] op_sel_hi:[1,0]
	v_pk_mul_f32 v[68:69], v[50:51], v[64:65] op_sel_hi:[1,0]
	v_pk_mul_f32 v[64:65], v[48:49], v[64:65] op_sel_hi:[1,0]
	v_cvt_pk_bf16_f32 v48, v60, v61
	v_cvt_pk_bf16_f32 v49, v62, v63
	v_cvt_pk_bf16_f32 v50, v56, v57
	v_cvt_pk_bf16_f32 v51, v58, v59
	v_cvt_pk_bf16_f32 v52, v52, v53
	v_cvt_pk_bf16_f32 v53, v54, v55
	v_cvt_pk_bf16_f32 v54, v64, v65
	v_cvt_pk_bf16_f32 v55, v68, v69
	flat_store_dwordx4 v[66:67], v[48:51]
	flat_store_dwordx4 v[66:67], v[52:55] offset:256
	s_nop 0
	v_add_u32_e32 v49, 0x90, v148
	v_mad_i64_i32 v[50:51], s[42:43], v49, s61, v[150:151]
	v_lshl_add_u64 v[50:51], v[50:51], 0, v[154:155]
	s_waitcnt lgkmcnt(0)
	v_fmamk_f32 v48, v203, 0x3b2aaaab, v174
	v_rsq_f32_e32 v48, v48
	s_nop 0
	v_pk_mul_f32 v[46:47], v[46:47], v[48:49] op_sel_hi:[1,0]
	v_pk_mul_f32 v[44:45], v[44:45], v[48:49] op_sel_hi:[1,0]
	v_pk_mul_f32 v[42:43], v[42:43], v[48:49] op_sel_hi:[1,0]
	v_pk_mul_f32 v[40:41], v[40:41], v[48:49] op_sel_hi:[1,0]
	v_pk_mul_f32 v[38:39], v[38:39], v[48:49] op_sel_hi:[1,0]
	v_pk_mul_f32 v[36:37], v[36:37], v[48:49] op_sel_hi:[1,0]
	v_pk_mul_f32 v[52:53], v[34:35], v[48:49] op_sel_hi:[1,0]
	v_pk_mul_f32 v[48:49], v[32:33], v[48:49] op_sel_hi:[1,0]
	v_cvt_pk_bf16_f32 v32, v44, v45
	v_cvt_pk_bf16_f32 v33, v46, v47
	v_cvt_pk_bf16_f32 v34, v40, v41
	v_cvt_pk_bf16_f32 v35, v42, v43
	v_cvt_pk_bf16_f32 v36, v36, v37
	v_cvt_pk_bf16_f32 v37, v38, v39
	v_cvt_pk_bf16_f32 v38, v48, v49
	v_cvt_pk_bf16_f32 v39, v52, v53
	flat_store_dwordx4 v[50:51], v[32:35]
	flat_store_dwordx4 v[50:51], v[36:39] offset:256
	s_nop 0
	v_add_u32_e32 v33, 0xa0, v148
	v_mad_i64_i32 v[34:35], s[42:43], v33, s61, v[150:151]
	v_lshl_add_u64 v[34:35], v[34:35], 0, v[154:155]
	s_waitcnt lgkmcnt(0)
	v_fmamk_f32 v32, v204, 0x3b2aaaab, v174
	v_rsq_f32_e32 v32, v32
	s_nop 0
	v_pk_mul_f32 v[30:31], v[30:31], v[32:33] op_sel_hi:[1,0]
	v_pk_mul_f32 v[28:29], v[28:29], v[32:33] op_sel_hi:[1,0]
	v_pk_mul_f32 v[26:27], v[26:27], v[32:33] op_sel_hi:[1,0]
	v_pk_mul_f32 v[24:25], v[24:25], v[32:33] op_sel_hi:[1,0]
	v_pk_mul_f32 v[22:23], v[22:23], v[32:33] op_sel_hi:[1,0]
	v_pk_mul_f32 v[20:21], v[20:21], v[32:33] op_sel_hi:[1,0]
	v_pk_mul_f32 v[36:37], v[18:19], v[32:33] op_sel_hi:[1,0]
	v_pk_mul_f32 v[32:33], v[16:17], v[32:33] op_sel_hi:[1,0]
	v_cvt_pk_bf16_f32 v16, v28, v29
	v_cvt_pk_bf16_f32 v17, v30, v31
	v_cvt_pk_bf16_f32 v18, v24, v25
	v_cvt_pk_bf16_f32 v19, v26, v27
	v_cvt_pk_bf16_f32 v20, v20, v21
	v_cvt_pk_bf16_f32 v21, v22, v23
	v_cvt_pk_bf16_f32 v22, v32, v33
	v_cvt_pk_bf16_f32 v23, v36, v37
	flat_store_dwordx4 v[34:35], v[16:19]
	flat_store_dwordx4 v[34:35], v[20:23] offset:256
	s_nop 0
	v_add_u32_e32 v17, 0xb0, v148
	v_mad_i64_i32 v[18:19], s[2:3], v17, s61, v[150:151]
	v_lshl_add_u64 v[18:19], v[18:19], 0, v[154:155]
	s_mov_b64 s[2:3], -1
	s_waitcnt lgkmcnt(0)
	v_fmamk_f32 v16, v205, 0x3b2aaaab, v174
	v_rsq_f32_e32 v16, v16
	s_nop 0
	v_pk_mul_f32 v[14:15], v[14:15], v[16:17] op_sel_hi:[1,0]
	v_pk_mul_f32 v[12:13], v[12:13], v[16:17] op_sel_hi:[1,0]
	v_pk_mul_f32 v[10:11], v[10:11], v[16:17] op_sel_hi:[1,0]
	v_pk_mul_f32 v[8:9], v[8:9], v[16:17] op_sel_hi:[1,0]
	v_pk_mul_f32 v[6:7], v[6:7], v[16:17] op_sel_hi:[1,0]
	v_pk_mul_f32 v[4:5], v[4:5], v[16:17] op_sel_hi:[1,0]
	v_pk_mul_f32 v[20:21], v[2:3], v[16:17] op_sel_hi:[1,0]
	v_pk_mul_f32 v[16:17], v[0:1], v[16:17] op_sel_hi:[1,0]
	v_cvt_pk_bf16_f32 v0, v12, v13
	v_cvt_pk_bf16_f32 v1, v14, v15
	v_cvt_pk_bf16_f32 v2, v8, v9
	v_cvt_pk_bf16_f32 v3, v10, v11
	v_cvt_pk_bf16_f32 v4, v4, v5
	v_cvt_pk_bf16_f32 v5, v6, v7
	v_cvt_pk_bf16_f32 v6, v16, v17
	v_cvt_pk_bf16_f32 v7, v20, v21
	flat_store_dwordx4 v[18:19], v[0:3]
	flat_store_dwordx4 v[18:19], v[4:7] offset:256
	s_cbranch_vccnz .LBB0_1193
	s_andn2_b64 vcc, exec, s[16:17]
	s_cbranch_vccnz .LBB0_1192
	s_barrier
	s_branch .LBB0_1192

; DI unsigned pk2(float lo, float hi) { typedef float v2f __attribute__((ext_vector_type(2))); typedef __bf16 v2b __attribute__((ext_vector_type(2))); v2f v = {lo, hi}; v2b b = __builtin_convertvector(v, v2b); return __builtin_bit_cast(unsigned, b); }
; DI unsigned f2bf(float f) { unsigned u = __builtin_bit_cast(unsigned, f); return (u + 0x7fffu + ((u >> 16) & 1u)) >> 16; }
;     DI void operator()(const f32x4 (&acc)[2][2][4][2], const Unit& u, int wr, int wc, int fr, int fq) const {
;         const int row0 = u.pm * 256 + wr * 64 + fr;
; #pragma unroll
;         for (int ai = 0; ai < 2; ++ai)
; #pragma unroll
;             for (int m = 0; m < 4; ++m) {
;                 const int row = row0 + ai * 128 + m * 16; const float rs = row_rstd<1>(P, row, 1.0f / 256.0f);
;                 const int b = row >> 13, s = row & 8191;
; #pragma unroll
;                 for (int bj = 0; bj < 2; ++bj) {
;                     const int h = u.pn * 2 + bj;
;                     const f32x4 a = acc[ai][bj][m][0] * rs, c = acc[ai][bj][m][1] * rs;
;                     if (wc < 2) {
;                         u32x4 w; w.x = pk2(a[0], a[1]); w.y = pk2(a[2], a[3]); w.z = pk2(c[0], c[1]); w.w = pk2(c[2], c[3]);
;                         *(u32x4*)(KN + (size_t)row * 512 + h * 64 + wc * 32 + 8 * fq) = w;
;                     } else {
;                         const unsigned vo = (unsigned)((b * 8 + h) * 64 + (wc - 2) * 32 + 8 * fq) * (unsigned)SEQ + (unsigned)s;
; #pragma unroll
;                         for (int i = 0; i < 4; ++i) { Vt[vo + (unsigned)(i * SEQ)] = (bf16_t)f2bf(a[i]); Vt[vo + (unsigned)((4 + i) * SEQ)] = (bf16_t)f2bf(c[i]); }
;                     }
.LBB0_1233:
	s_lshl_b32 s4, s14, 8
	s_add_i32 s12, s4, s68
	v_or_b32_e32 v152, s12, v129
	v_ashrrev_i32_e32 v153, 31, v152
	v_lshl_add_u64 v[154:155], v[152:153], 2, s[18:19]
	global_load_dword v198, v[154:155], off
	global_load_dword v199, v[154:155], off offset:64
	global_load_dword v200, v[154:155], off offset:128
	global_load_dword v201, v[154:155], off offset:192
	global_load_dword v202, v[154:155], off offset:512
	global_load_dword v203, v[154:155], off offset:576
	global_load_dword v204, v[154:155], off offset:640
	global_load_dword v205, v[154:155], off offset:704
	s_lshr_b32 s12, s12, 10
	s_lshl_b32 s51, s60, 1
	s_mov_b64 s[4:5], -1
	s_and_b64 vcc, exec, s[42:43]
	s_and_b32 s52, s12, 0x1ff8
	v_and_or_b32 v168, v152, s75, v163
	s_waitcnt vmcnt(0) lgkmcnt(0)
	v_fmamk_f32 v140, v198, 0x3b800000, v167
	v_rsq_f32_e32 v156, v140
	s_nop 0
	v_pk_mul_f32 v[122:123], v[122:123], v[156:157] op_sel_hi:[1,0]
	v_pk_mul_f32 v[158:159], v[120:121], v[156:157] op_sel_hi:[1,0]
	v_pk_mul_f32 v[126:127], v[126:127], v[156:157] op_sel_hi:[1,0]
	v_pk_mul_f32 v[124:125], v[124:125], v[156:157] op_sel_hi:[1,0]
	s_cbranch_vccz .LBB0_1235
	s_add_i32 s4, s52, s51
	v_lshl_add_u32 v140, s4, 19, v168
	v_bfe_u32 v120, v158, 16, 1
	v_add3_u32 v157, v158, v120, s76
	v_lshl_add_u64 v[120:121], v[140:141], 1, s[22:23]
	flat_store_short_d16_hi v[120:121], v157
	v_bfe_u32 v120, v124, 16, 1
	v_add3_u32 v157, v124, v120, s76
	v_or_b32_e32 v120, 0x8000, v140
	v_mov_b32_e32 v121, v141
	v_lshl_add_u64 v[120:121], v[120:121], 1, s[22:23]
	flat_store_short_d16_hi v[120:121], v157
	v_bfe_u32 v120, v159, 16, 1
	v_add3_u32 v157, v159, v120, s76
	v_or_b32_e32 v120, 0x2000, v140
	v_mov_b32_e32 v121, v141
	v_lshl_add_u64 v[120:121], v[120:121], 1, s[22:23]
	flat_store_short_d16_hi v[120:121], v157
	v_bfe_u32 v120, v125, 16, 1
	v_add3_u32 v157, v125, v120, s76
	v_or_b32_e32 v120, 0xa000, v140
	v_mov_b32_e32 v121, v141
	v_lshl_add_u64 v[120:121], v[120:121], 1, s[22:23]
	flat_store_short_d16_hi v[120:121], v157
	v_bfe_u32 v120, v122, 16, 1
	v_add3_u32 v157, v122, v120, s76
	v_or_b32_e32 v120, 0x4000, v140
	v_mov_b32_e32 v121, v141
	v_lshl_add_u64 v[120:121], v[120:121], 1, s[22:23]
	flat_store_short_d16_hi v[120:121], v157
	v_bfe_u32 v120, v126, 16, 1
	v_add3_u32 v157, v126, v120, s76
	v_or_b32_e32 v120, 0xc000, v140
	v_mov_b32_e32 v121, v141
	v_lshl_add_u64 v[120:121], v[120:121], 1, s[22:23]
	flat_store_short_d16_hi v[120:121], v157
	v_bfe_u32 v120, v123, 16, 1
	v_add3_u32 v157, v123, v120, s76
	v_or_b32_e32 v120, 0x6000, v140
	v_mov_b32_e32 v121, v141
	v_lshl_add_u64 v[120:121], v[120:121], 1, s[22:23]
	flat_store_short_d16_hi v[120:121], v157
	v_bfe_u32 v120, v127, 16, 1
	v_or_b32_e32 v140, 0xe000, v140
	v_add3_u32 v157, v127, v120, s76
	v_lshl_add_u64 v[120:121], v[140:141], 1, s[22:23]
	flat_store_short_d16_hi v[120:121], v157
	s_mov_b64 s[4:5], 0

; DI unsigned f2bf(float f) { unsigned u = __builtin_bit_cast(unsigned, f); return (u + 0x7fffu + ((u >> 16) & 1u)) >> 16; }
; DI unsigned pk2(float lo, float hi) { typedef float v2f __attribute__((ext_vector_type(2))); typedef __bf16 v2b __attribute__((ext_vector_type(2))); v2f v = {lo, hi}; v2b b = __builtin_convertvector(v, v2b); return __builtin_bit_cast(unsigned, b); }
;     DI void operator()(const f32x4 (&acc)[2][2][4][2], const Unit& u, int wr, int wc, int fr, int fq) const {
;     ...
;                 const int row = row0 + ai * 128 + m * 16; const float rs = row_rstd<1>(P, row, 1.0f / 256.0f);
;                 const int b = row >> 13, s = row & 8191;
; #pragma unroll
;                 for (int bj = 0; bj < 2; ++bj) {
;                     const int h = u.pn * 2 + bj;
;                     const f32x4 a = acc[ai][bj][m][0] * rs, c = acc[ai][bj][m][1] * rs;
;                     if (wc < 2) {
;                         u32x4 w; w.x = pk2(a[0], a[1]); w.y = pk2(a[2], a[3]); w.z = pk2(c[0], c[1]); w.w = pk2(c[2], c[3]);
;                         *(u32x4*)(KN + (size_t)row * 512 + h * 64 + wc * 32 + 8 * fq) = w;
;                     } else {
;                         const unsigned vo = (unsigned)((b * 8 + h) * 64 + (wc - 2) * 32 + 8 * fq) * (unsigned)SEQ + (unsigned)s;
; #pragma unroll
;                         for (int i = 0; i < 4; ++i) { Vt[vo + (unsigned)(i * SEQ)] = (bf16_t)f2bf(a[i]); Vt[vo + (unsigned)((4 + i) * SEQ)] = (bf16_t)f2bf(c[i]); }
.LBB0_1241:
	v_or_b32_e32 v114, 16, v152
	v_ashrrev_i32_e32 v115, 31, v114
	v_lshl_add_u64 v[112:113], v[114:115], 2, s[18:19]
	s_nop 0
	s_and_b64 vcc, exec, s[4:5]
	v_and_or_b32 v118, v114, s77, v163
	s_mov_b64 s[12:13], -1
	s_waitcnt lgkmcnt(0)
	v_fmamk_f32 v112, v199, 0x3b800000, v167
	v_rsq_f32_e32 v112, v112
	s_nop 0
	v_pk_mul_f32 v[110:111], v[110:111], v[112:113] op_sel_hi:[1,0]
	v_pk_mul_f32 v[108:109], v[108:109], v[112:113] op_sel_hi:[1,0]
	v_pk_mul_f32 v[106:107], v[106:107], v[112:113] op_sel_hi:[1,0]
	v_pk_mul_f32 v[116:117], v[104:105], v[112:113] op_sel_hi:[1,0]
	s_cbranch_vccnz .LBB0_1243
	s_add_i32 s12, s52, s51
	v_bfe_u32 v105, v108, 16, 1
	v_lshl_add_u32 v104, s12, 19, v118
	v_add3_u32 v113, v108, v105, s76
	v_mov_b32_e32 v105, v141
	v_lshl_add_u64 v[120:121], v[104:105], 1, s[22:23]
	flat_store_short_d16_hi v[120:121], v113
	v_bfe_u32 v105, v116, 16, 1
	v_or_b32_e32 v120, 0x8000, v104
	v_mov_b32_e32 v121, v141
	v_add3_u32 v105, v116, v105, s76
	v_lshl_add_u64 v[120:121], v[120:121], 1, s[22:23]
	flat_store_short_d16_hi v[120:121], v105
	v_bfe_u32 v105, v109, 16, 1
	v_or_b32_e32 v120, 0x2000, v104
	v_mov_b32_e32 v121, v141
	v_add3_u32 v105, v109, v105, s76
	v_lshl_add_u64 v[120:121], v[120:121], 1, s[22:23]
	flat_store_short_d16_hi v[120:121], v105
	v_bfe_u32 v105, v117, 16, 1
	v_or_b32_e32 v120, 0xa000, v104
	v_mov_b32_e32 v121, v141
	v_add3_u32 v105, v117, v105, s76
	v_lshl_add_u64 v[120:121], v[120:121], 1, s[22:23]
	flat_store_short_d16_hi v[120:121], v105
	v_bfe_u32 v105, v110, 16, 1
	v_or_b32_e32 v120, 0x4000, v104
	v_mov_b32_e32 v121, v141
	v_add3_u32 v105, v110, v105, s76
	v_lshl_add_u64 v[120:121], v[120:121], 1, s[22:23]
	flat_store_short_d16_hi v[120:121], v105
	v_bfe_u32 v105, v106, 16, 1
	v_or_b32_e32 v120, 0xc000, v104
	v_mov_b32_e32 v121, v141
	v_add3_u32 v105, v106, v105, s76
	v_lshl_add_u64 v[120:121], v[120:121], 1, s[22:23]
	flat_store_short_d16_hi v[120:121], v105
	v_bfe_u32 v105, v111, 16, 1
	v_or_b32_e32 v120, 0x6000, v104
	v_mov_b32_e32 v121, v141
	v_add3_u32 v105, v111, v105, s76
	v_lshl_add_u64 v[120:121], v[120:121], 1, s[22:23]
	flat_store_short_d16_hi v[120:121], v105
	v_bfe_u32 v105, v107, 16, 1
	v_add3_u32 v113, v107, v105, s76
	v_or_b32_e32 v104, 0xe000, v104
	v_mov_b32_e32 v105, v141
	v_lshl_add_u64 v[104:105], v[104:105], 1, s[22:23]
	s_mov_b64 s[12:13], 0
	flat_store_short_d16_hi v[104:105], v113

; DI unsigned f2bf(float f) { unsigned u = __builtin_bit_cast(unsigned, f); return (u + 0x7fffu + ((u >> 16) & 1u)) >> 16; }
; DI unsigned pk2(float lo, float hi) { typedef float v2f __attribute__((ext_vector_type(2))); typedef __bf16 v2b __attribute__((ext_vector_type(2))); v2f v = {lo, hi}; v2b b = __builtin_convertvector(v, v2b); return __builtin_bit_cast(unsigned, b); }
;     DI void operator()(const f32x4 (&acc)[2][2][4][2], const Unit& u, int wr, int wc, int fr, int fq) const {
;     ...
;                 const int row = row0 + ai * 128 + m * 16; const float rs = row_rstd<1>(P, row, 1.0f / 256.0f);
;                 const int b = row >> 13, s = row & 8191;
; #pragma unroll
;                 for (int bj = 0; bj < 2; ++bj) {
;                     const int h = u.pn * 2 + bj;
;                     const f32x4 a = acc[ai][bj][m][0] * rs, c = acc[ai][bj][m][1] * rs;
;                     if (wc < 2) {
;                         u32x4 w; w.x = pk2(a[0], a[1]); w.y = pk2(a[2], a[3]); w.z = pk2(c[0], c[1]); w.w = pk2(c[2], c[3]);
;                         *(u32x4*)(KN + (size_t)row * 512 + h * 64 + wc * 32 + 8 * fq) = w;
;                     } else {
;                         const unsigned vo = (unsigned)((b * 8 + h) * 64 + (wc - 2) * 32 + 8 * fq) * (unsigned)SEQ + (unsigned)s;
; #pragma unroll
;                         for (int i = 0; i < 4; ++i) { Vt[vo + (unsigned)(i * SEQ)] = (bf16_t)f2bf(a[i]); Vt[vo + (unsigned)((4 + i) * SEQ)] = (bf16_t)f2bf(c[i]); }
.LBB0_1249:
	v_or_b32_e32 v98, 32, v152
	v_ashrrev_i32_e32 v99, 31, v98
	v_lshl_add_u64 v[96:97], v[98:99], 2, s[18:19]
	s_nop 0
	s_and_b64 vcc, exec, s[4:5]
	v_and_or_b32 v102, v98, s78, v163
	s_mov_b64 s[12:13], -1
	s_waitcnt lgkmcnt(0)
	v_fmamk_f32 v96, v200, 0x3b800000, v167
	v_rsq_f32_e32 v96, v96
	s_nop 0
	v_pk_mul_f32 v[94:95], v[94:95], v[96:97] op_sel_hi:[1,0]
	v_pk_mul_f32 v[92:93], v[92:93], v[96:97] op_sel_hi:[1,0]
	v_pk_mul_f32 v[90:91], v[90:91], v[96:97] op_sel_hi:[1,0]
	v_pk_mul_f32 v[100:101], v[88:89], v[96:97] op_sel_hi:[1,0]
	s_cbranch_vccnz .LBB0_1251
	s_add_i32 s12, s52, s51
	v_bfe_u32 v89, v92, 16, 1
	v_lshl_add_u32 v88, s12, 19, v102
	v_add3_u32 v97, v92, v89, s76
	v_mov_b32_e32 v89, v141
	v_lshl_add_u64 v[104:105], v[88:89], 1, s[22:23]
	flat_store_short_d16_hi v[104:105], v97
	v_bfe_u32 v89, v100, 16, 1
	v_or_b32_e32 v104, 0x8000, v88
	v_mov_b32_e32 v105, v141
	v_add3_u32 v89, v100, v89, s76
	v_lshl_add_u64 v[104:105], v[104:105], 1, s[22:23]
	flat_store_short_d16_hi v[104:105], v89
	v_bfe_u32 v89, v93, 16, 1
	v_or_b32_e32 v104, 0x2000, v88
	v_mov_b32_e32 v105, v141
	v_add3_u32 v89, v93, v89, s76
	v_lshl_add_u64 v[104:105], v[104:105], 1, s[22:23]
	flat_store_short_d16_hi v[104:105], v89
	v_bfe_u32 v89, v101, 16, 1
	v_or_b32_e32 v104, 0xa000, v88
	v_mov_b32_e32 v105, v141
	v_add3_u32 v89, v101, v89, s76
	v_lshl_add_u64 v[104:105], v[104:105], 1, s[22:23]
	flat_store_short_d16_hi v[104:105], v89
	v_bfe_u32 v89, v94, 16, 1
	v_or_b32_e32 v104, 0x4000, v88
	v_mov_b32_e32 v105, v141
	v_add3_u32 v89, v94, v89, s76
	v_lshl_add_u64 v[104:105], v[104:105], 1, s[22:23]
	flat_store_short_d16_hi v[104:105], v89
	v_bfe_u32 v89, v90, 16, 1
	v_or_b32_e32 v104, 0xc000, v88
	v_mov_b32_e32 v105, v141
	v_add3_u32 v89, v90, v89, s76
	v_lshl_add_u64 v[104:105], v[104:105], 1, s[22:23]
	flat_store_short_d16_hi v[104:105], v89
	v_bfe_u32 v89, v95, 16, 1
	v_or_b32_e32 v104, 0x6000, v88
	v_mov_b32_e32 v105, v141
	v_add3_u32 v89, v95, v89, s76
	v_lshl_add_u64 v[104:105], v[104:105], 1, s[22:23]
	flat_store_short_d16_hi v[104:105], v89
	v_bfe_u32 v89, v91, 16, 1
	v_add3_u32 v97, v91, v89, s76
	v_or_b32_e32 v88, 0xe000, v88
	v_mov_b32_e32 v89, v141
	v_lshl_add_u64 v[88:89], v[88:89], 1, s[22:23]
	s_mov_b64 s[12:13], 0
	flat_store_short_d16_hi v[88:89], v97

; DI unsigned f2bf(float f) { unsigned u = __builtin_bit_cast(unsigned, f); return (u + 0x7fffu + ((u >> 16) & 1u)) >> 16; }
; DI unsigned pk2(float lo, float hi) { typedef float v2f __attribute__((ext_vector_type(2))); typedef __bf16 v2b __attribute__((ext_vector_type(2))); v2f v = {lo, hi}; v2b b = __builtin_convertvector(v, v2b); return __builtin_bit_cast(unsigned, b); }
;     DI void operator()(const f32x4 (&acc)[2][2][4][2], const Unit& u, int wr, int wc, int fr, int fq) const {
;     ...
;                 const int row = row0 + ai * 128 + m * 16; const float rs = row_rstd<1>(P, row, 1.0f / 256.0f);
;                 const int b = row >> 13, s = row & 8191;
; #pragma unroll
;                 for (int bj = 0; bj < 2; ++bj) {
;                     const int h = u.pn * 2 + bj;
;                     const f32x4 a = acc[ai][bj][m][0] * rs, c = acc[ai][bj][m][1] * rs;
;                     if (wc < 2) {
;                         u32x4 w; w.x = pk2(a[0], a[1]); w.y = pk2(a[2], a[3]); w.z = pk2(c[0], c[1]); w.w = pk2(c[2], c[3]);
;                         *(u32x4*)(KN + (size_t)row * 512 + h * 64 + wc * 32 + 8 * fq) = w;
;                     } else {
;                         const unsigned vo = (unsigned)((b * 8 + h) * 64 + (wc - 2) * 32 + 8 * fq) * (unsigned)SEQ + (unsigned)s;
; #pragma unroll
;                         for (int i = 0; i < 4; ++i) { Vt[vo + (unsigned)(i * SEQ)] = (bf16_t)f2bf(a[i]); Vt[vo + (unsigned)((4 + i) * SEQ)] = (bf16_t)f2bf(c[i]); }
.LBB0_1257:
	v_or_b32_e32 v82, 48, v152
	v_ashrrev_i32_e32 v83, 31, v82
	v_lshl_add_u64 v[80:81], v[82:83], 2, s[18:19]
	s_nop 0
	s_and_b64 vcc, exec, s[4:5]
	v_and_or_b32 v86, v82, s79, v163
	s_mov_b64 s[12:13], -1
	s_waitcnt lgkmcnt(0)
	v_fmamk_f32 v80, v201, 0x3b800000, v167
	v_rsq_f32_e32 v80, v80
	s_nop 0
	v_pk_mul_f32 v[78:79], v[78:79], v[80:81] op_sel_hi:[1,0]
	v_pk_mul_f32 v[76:77], v[76:77], v[80:81] op_sel_hi:[1,0]
	v_pk_mul_f32 v[74:75], v[74:75], v[80:81] op_sel_hi:[1,0]
	v_pk_mul_f32 v[84:85], v[72:73], v[80:81] op_sel_hi:[1,0]
	s_cbranch_vccnz .LBB0_1259
	s_add_i32 s12, s52, s51
	v_bfe_u32 v73, v76, 16, 1
	v_lshl_add_u32 v72, s12, 19, v86
	v_add3_u32 v81, v76, v73, s76
	v_mov_b32_e32 v73, v141
	v_lshl_add_u64 v[88:89], v[72:73], 1, s[22:23]
	flat_store_short_d16_hi v[88:89], v81
	v_bfe_u32 v73, v84, 16, 1
	v_or_b32_e32 v88, 0x8000, v72
	v_mov_b32_e32 v89, v141
	v_add3_u32 v73, v84, v73, s76
	v_lshl_add_u64 v[88:89], v[88:89], 1, s[22:23]
	flat_store_short_d16_hi v[88:89], v73
	v_bfe_u32 v73, v77, 16, 1
	v_or_b32_e32 v88, 0x2000, v72
	v_mov_b32_e32 v89, v141
	v_add3_u32 v73, v77, v73, s76
	v_lshl_add_u64 v[88:89], v[88:89], 1, s[22:23]
	flat_store_short_d16_hi v[88:89], v73
	v_bfe_u32 v73, v85, 16, 1
	v_or_b32_e32 v88, 0xa000, v72
	v_mov_b32_e32 v89, v141
	v_add3_u32 v73, v85, v73, s76
	v_lshl_add_u64 v[88:89], v[88:89], 1, s[22:23]
	flat_store_short_d16_hi v[88:89], v73
	v_bfe_u32 v73, v78, 16, 1
	v_or_b32_e32 v88, 0x4000, v72
	v_mov_b32_e32 v89, v141
	v_add3_u32 v73, v78, v73, s76
	v_lshl_add_u64 v[88:89], v[88:89], 1, s[22:23]
	flat_store_short_d16_hi v[88:89], v73
	v_bfe_u32 v73, v74, 16, 1
	v_or_b32_e32 v88, 0xc000, v72
	v_mov_b32_e32 v89, v141
	v_add3_u32 v73, v74, v73, s76
	v_lshl_add_u64 v[88:89], v[88:89], 1, s[22:23]
	flat_store_short_d16_hi v[88:89], v73
	v_bfe_u32 v73, v79, 16, 1
	v_or_b32_e32 v88, 0x6000, v72
	v_mov_b32_e32 v89, v141
	v_add3_u32 v73, v79, v73, s76
	v_lshl_add_u64 v[88:89], v[88:89], 1, s[22:23]
	flat_store_short_d16_hi v[88:89], v73
	v_bfe_u32 v73, v75, 16, 1
	v_add3_u32 v81, v75, v73, s76
	v_or_b32_e32 v72, 0xe000, v72
	v_mov_b32_e32 v73, v141
	v_lshl_add_u64 v[72:73], v[72:73], 1, s[22:23]
	s_mov_b64 s[12:13], 0
	flat_store_short_d16_hi v[72:73], v81

; DI unsigned f2bf(float f) { unsigned u = __builtin_bit_cast(unsigned, f); return (u + 0x7fffu + ((u >> 16) & 1u)) >> 16; }
; DI unsigned pk2(float lo, float hi) { typedef float v2f __attribute__((ext_vector_type(2))); typedef __bf16 v2b __attribute__((ext_vector_type(2))); v2f v = {lo, hi}; v2b b = __builtin_convertvector(v, v2b); return __builtin_bit_cast(unsigned, b); }
;     DI void operator()(const f32x4 (&acc)[2][2][4][2], const Unit& u, int wr, int wc, int fr, int fq) const {
;     ...
;                 const int row = row0 + ai * 128 + m * 16; const float rs = row_rstd<1>(P, row, 1.0f / 256.0f);
;                 const int b = row >> 13, s = row & 8191;
; #pragma unroll
;                 for (int bj = 0; bj < 2; ++bj) {
;                     const int h = u.pn * 2 + bj;
;                     const f32x4 a = acc[ai][bj][m][0] * rs, c = acc[ai][bj][m][1] * rs;
;                     if (wc < 2) {
;                         u32x4 w; w.x = pk2(a[0], a[1]); w.y = pk2(a[2], a[3]); w.z = pk2(c[0], c[1]); w.w = pk2(c[2], c[3]);
;                         *(u32x4*)(KN + (size_t)row * 512 + h * 64 + wc * 32 + 8 * fq) = w;
;                     } else {
;                         const unsigned vo = (unsigned)((b * 8 + h) * 64 + (wc - 2) * 32 + 8 * fq) * (unsigned)SEQ + (unsigned)s;
; #pragma unroll
;                         for (int i = 0; i < 4; ++i) { Vt[vo + (unsigned)(i * SEQ)] = (bf16_t)f2bf(a[i]); Vt[vo + (unsigned)((4 + i) * SEQ)] = (bf16_t)f2bf(c[i]); }
.LBB0_1265:
	s_nop 0
	v_add_u32_e32 v66, 0x80, v152
	v_lshrrev_b32_e32 v65, 10, v66
	v_and_b32_e32 v72, 0x1ff8, v65
	s_mov_b64 s[12:13], -1
	s_and_b64 vcc, exec, s[4:5]
	v_and_or_b32 v71, v66, s75, v163
	v_add_u32_e32 v70, s51, v72
	s_waitcnt lgkmcnt(0)
	v_fmamk_f32 v64, v202, 0x3b800000, v167
	v_rsq_f32_e32 v64, v64
	s_nop 0
	v_pk_mul_f32 v[62:63], v[62:63], v[64:65] op_sel_hi:[1,0]
	v_pk_mul_f32 v[60:61], v[60:61], v[64:65] op_sel_hi:[1,0]
	v_pk_mul_f32 v[58:59], v[58:59], v[64:65] op_sel_hi:[1,0]
	v_pk_mul_f32 v[68:69], v[56:57], v[64:65] op_sel_hi:[1,0]
	s_cbranch_vccnz .LBB0_1267
	v_bfe_u32 v57, v60, 16, 1
	v_lshl_add_u32 v56, v70, 19, v71
	v_add3_u32 v65, v60, v57, s76
	v_mov_b32_e32 v57, v141
	v_lshl_add_u64 v[74:75], v[56:57], 1, s[22:23]
	flat_store_short_d16_hi v[74:75], v65
	v_bfe_u32 v57, v68, 16, 1
	v_or_b32_e32 v74, 0x8000, v56
	v_mov_b32_e32 v75, v141
	v_add3_u32 v57, v68, v57, s76
	v_lshl_add_u64 v[74:75], v[74:75], 1, s[22:23]
	flat_store_short_d16_hi v[74:75], v57
	v_bfe_u32 v57, v61, 16, 1
	v_or_b32_e32 v74, 0x2000, v56
	v_mov_b32_e32 v75, v141
	v_add3_u32 v57, v61, v57, s76
	v_lshl_add_u64 v[74:75], v[74:75], 1, s[22:23]
	flat_store_short_d16_hi v[74:75], v57
	v_bfe_u32 v57, v69, 16, 1
	v_or_b32_e32 v74, 0xa000, v56
	v_mov_b32_e32 v75, v141
	v_add3_u32 v57, v69, v57, s76
	v_lshl_add_u64 v[74:75], v[74:75], 1, s[22:23]
	flat_store_short_d16_hi v[74:75], v57
	v_bfe_u32 v57, v62, 16, 1
	v_or_b32_e32 v74, 0x4000, v56
	v_mov_b32_e32 v75, v141
	v_add3_u32 v57, v62, v57, s76
	v_lshl_add_u64 v[74:75], v[74:75], 1, s[22:23]
	flat_store_short_d16_hi v[74:75], v57
	v_bfe_u32 v57, v58, 16, 1
	v_or_b32_e32 v74, 0xc000, v56
	v_mov_b32_e32 v75, v141
	v_add3_u32 v57, v58, v57, s76
	v_lshl_add_u64 v[74:75], v[74:75], 1, s[22:23]
	flat_store_short_d16_hi v[74:75], v57
	v_bfe_u32 v57, v63, 16, 1
	v_or_b32_e32 v74, 0x6000, v56
	v_mov_b32_e32 v75, v141
	v_add3_u32 v57, v63, v57, s76
	v_lshl_add_u64 v[74:75], v[74:75], 1, s[22:23]
	flat_store_short_d16_hi v[74:75], v57
	v_bfe_u32 v57, v59, 16, 1
	v_add3_u32 v65, v59, v57, s76
	v_or_b32_e32 v56, 0xe000, v56
	v_mov_b32_e32 v57, v141
	v_lshl_add_u64 v[56:57], v[56:57], 1, s[22:23]
	s_mov_b64 s[12:13], 0
	flat_store_short_d16_hi v[56:57], v65

; DI unsigned f2bf(float f) { unsigned u = __builtin_bit_cast(unsigned, f); return (u + 0x7fffu + ((u >> 16) & 1u)) >> 16; }
; DI unsigned pk2(float lo, float hi) { typedef float v2f __attribute__((ext_vector_type(2))); typedef __bf16 v2b __attribute__((ext_vector_type(2))); v2f v = {lo, hi}; v2b b = __builtin_convertvector(v, v2b); return __builtin_bit_cast(unsigned, b); }
;     DI void operator()(const f32x4 (&acc)[2][2][4][2], const Unit& u, int wr, int wc, int fr, int fq) const {
;     ...
;                 const int row = row0 + ai * 128 + m * 16; const float rs = row_rstd<1>(P, row, 1.0f / 256.0f);
;                 const int b = row >> 13, s = row & 8191;
; #pragma unroll
;                 for (int bj = 0; bj < 2; ++bj) {
;                     const int h = u.pn * 2 + bj;
;                     const f32x4 a = acc[ai][bj][m][0] * rs, c = acc[ai][bj][m][1] * rs;
;                     if (wc < 2) {
;                         u32x4 w; w.x = pk2(a[0], a[1]); w.y = pk2(a[2], a[3]); w.z = pk2(c[0], c[1]); w.w = pk2(c[2], c[3]);
;                         *(u32x4*)(KN + (size_t)row * 512 + h * 64 + wc * 32 + 8 * fq) = w;
;                     } else {
;                         const unsigned vo = (unsigned)((b * 8 + h) * 64 + (wc - 2) * 32 + 8 * fq) * (unsigned)SEQ + (unsigned)s;
; #pragma unroll
;                         for (int i = 0; i < 4; ++i) { Vt[vo + (unsigned)(i * SEQ)] = (bf16_t)f2bf(a[i]); Vt[vo + (unsigned)((4 + i) * SEQ)] = (bf16_t)f2bf(c[i]); }
.LBB0_1273:
	s_nop 0
	v_add_u32_e32 v50, 0x90, v152
	s_and_b64 vcc, exec, s[4:5]
	v_and_or_b32 v54, v50, s77, v163
	s_mov_b64 s[12:13], -1
	s_waitcnt lgkmcnt(0)
	v_fmamk_f32 v48, v203, 0x3b800000, v167
	v_rsq_f32_e32 v48, v48
	s_nop 0
	v_pk_mul_f32 v[46:47], v[46:47], v[48:49] op_sel_hi:[1,0]
	v_pk_mul_f32 v[44:45], v[44:45], v[48:49] op_sel_hi:[1,0]
	v_pk_mul_f32 v[42:43], v[42:43], v[48:49] op_sel_hi:[1,0]
	v_pk_mul_f32 v[52:53], v[40:41], v[48:49] op_sel_hi:[1,0]
	s_cbranch_vccnz .LBB0_1275
	v_bfe_u32 v41, v44, 16, 1
	v_lshl_add_u32 v40, v70, 19, v54
	v_add3_u32 v49, v44, v41, s76
	v_mov_b32_e32 v41, v141
	v_lshl_add_u64 v[56:57], v[40:41], 1, s[22:23]
	flat_store_short_d16_hi v[56:57], v49
	v_bfe_u32 v41, v52, 16, 1
	v_or_b32_e32 v56, 0x8000, v40
	v_mov_b32_e32 v57, v141
	v_add3_u32 v41, v52, v41, s76
	v_lshl_add_u64 v[56:57], v[56:57], 1, s[22:23]
	flat_store_short_d16_hi v[56:57], v41
	v_bfe_u32 v41, v45, 16, 1
	v_or_b32_e32 v56, 0x2000, v40
	v_mov_b32_e32 v57, v141
	v_add3_u32 v41, v45, v41, s76
	v_lshl_add_u64 v[56:57], v[56:57], 1, s[22:23]
	flat_store_short_d16_hi v[56:57], v41
	v_bfe_u32 v41, v53, 16, 1
	v_or_b32_e32 v56, 0xa000, v40
	v_mov_b32_e32 v57, v141
	v_add3_u32 v41, v53, v41, s76
	v_lshl_add_u64 v[56:57], v[56:57], 1, s[22:23]
	flat_store_short_d16_hi v[56:57], v41
	v_bfe_u32 v41, v46, 16, 1
	v_or_b32_e32 v56, 0x4000, v40
	v_mov_b32_e32 v57, v141
	v_add3_u32 v41, v46, v41, s76
	v_lshl_add_u64 v[56:57], v[56:57], 1, s[22:23]
	flat_store_short_d16_hi v[56:57], v41
	v_bfe_u32 v41, v42, 16, 1
	v_or_b32_e32 v56, 0xc000, v40
	v_mov_b32_e32 v57, v141
	v_add3_u32 v41, v42, v41, s76
	v_lshl_add_u64 v[56:57], v[56:57], 1, s[22:23]
	flat_store_short_d16_hi v[56:57], v41
	v_bfe_u32 v41, v47, 16, 1
	v_or_b32_e32 v56, 0x6000, v40
	v_mov_b32_e32 v57, v141
	v_add3_u32 v41, v47, v41, s76
	v_lshl_add_u64 v[56:57], v[56:57], 1, s[22:23]
	flat_store_short_d16_hi v[56:57], v41
	v_bfe_u32 v41, v43, 16, 1
	v_add3_u32 v49, v43, v41, s76
	v_or_b32_e32 v40, 0xe000, v40
	v_mov_b32_e32 v41, v141
	v_lshl_add_u64 v[40:41], v[40:41], 1, s[22:23]
	s_mov_b64 s[12:13], 0
	flat_store_short_d16_hi v[40:41], v49

; DI unsigned f2bf(float f) { unsigned u = __builtin_bit_cast(unsigned, f); return (u + 0x7fffu + ((u >> 16) & 1u)) >> 16; }
; DI unsigned pk2(float lo, float hi) { typedef float v2f __attribute__((ext_vector_type(2))); typedef __bf16 v2b __attribute__((ext_vector_type(2))); v2f v = {lo, hi}; v2b b = __builtin_convertvector(v, v2b); return __builtin_bit_cast(unsigned, b); }
;     DI void operator()(const f32x4 (&acc)[2][2][4][2], const Unit& u, int wr, int wc, int fr, int fq) const {
;     ...
;                 const int row = row0 + ai * 128 + m * 16; const float rs = row_rstd<1>(P, row, 1.0f / 256.0f);
;                 const int b = row >> 13, s = row & 8191;
; #pragma unroll
;                 for (int bj = 0; bj < 2; ++bj) {
;                     const int h = u.pn * 2 + bj;
;                     const f32x4 a = acc[ai][bj][m][0] * rs, c = acc[ai][bj][m][1] * rs;
;                     if (wc < 2) {
;                         u32x4 w; w.x = pk2(a[0], a[1]); w.y = pk2(a[2], a[3]); w.z = pk2(c[0], c[1]); w.w = pk2(c[2], c[3]);
;                         *(u32x4*)(KN + (size_t)row * 512 + h * 64 + wc * 32 + 8 * fq) = w;
;                     } else {
;                         const unsigned vo = (unsigned)((b * 8 + h) * 64 + (wc - 2) * 32 + 8 * fq) * (unsigned)SEQ + (unsigned)s;
; #pragma unroll
;                         for (int i = 0; i < 4; ++i) { Vt[vo + (unsigned)(i * SEQ)] = (bf16_t)f2bf(a[i]); Vt[vo + (unsigned)((4 + i) * SEQ)] = (bf16_t)f2bf(c[i]); }
.LBB0_1281:
	s_nop 0
	v_add_u32_e32 v34, 0xa0, v152
	s_and_b64 vcc, exec, s[4:5]
	v_and_or_b32 v38, v34, s78, v163
	s_mov_b64 s[12:13], -1
	s_waitcnt lgkmcnt(0)
	v_fmamk_f32 v32, v204, 0x3b800000, v167
	v_rsq_f32_e32 v32, v32
	s_nop 0
	v_pk_mul_f32 v[30:31], v[30:31], v[32:33] op_sel_hi:[1,0]
	v_pk_mul_f32 v[28:29], v[28:29], v[32:33] op_sel_hi:[1,0]
	v_pk_mul_f32 v[26:27], v[26:27], v[32:33] op_sel_hi:[1,0]
	v_pk_mul_f32 v[36:37], v[24:25], v[32:33] op_sel_hi:[1,0]
	s_cbranch_vccnz .LBB0_1283
	v_bfe_u32 v25, v28, 16, 1
	v_lshl_add_u32 v24, v70, 19, v38
	v_add3_u32 v33, v28, v25, s76
	v_mov_b32_e32 v25, v141
	v_lshl_add_u64 v[40:41], v[24:25], 1, s[22:23]
	flat_store_short_d16_hi v[40:41], v33
	v_bfe_u32 v25, v36, 16, 1
	v_or_b32_e32 v40, 0x8000, v24
	v_mov_b32_e32 v41, v141
	v_add3_u32 v25, v36, v25, s76
	v_lshl_add_u64 v[40:41], v[40:41], 1, s[22:23]
	flat_store_short_d16_hi v[40:41], v25
	v_bfe_u32 v25, v29, 16, 1
	v_or_b32_e32 v40, 0x2000, v24
	v_mov_b32_e32 v41, v141
	v_add3_u32 v25, v29, v25, s76
	v_lshl_add_u64 v[40:41], v[40:41], 1, s[22:23]
	flat_store_short_d16_hi v[40:41], v25
	v_bfe_u32 v25, v37, 16, 1
	v_or_b32_e32 v40, 0xa000, v24
	v_mov_b32_e32 v41, v141
	v_add3_u32 v25, v37, v25, s76
	v_lshl_add_u64 v[40:41], v[40:41], 1, s[22:23]
	flat_store_short_d16_hi v[40:41], v25
	v_bfe_u32 v25, v30, 16, 1
	v_or_b32_e32 v40, 0x4000, v24
	v_mov_b32_e32 v41, v141
	v_add3_u32 v25, v30, v25, s76
	v_lshl_add_u64 v[40:41], v[40:41], 1, s[22:23]
	flat_store_short_d16_hi v[40:41], v25
	v_bfe_u32 v25, v26, 16, 1
	v_or_b32_e32 v40, 0xc000, v24
	v_mov_b32_e32 v41, v141
	v_add3_u32 v25, v26, v25, s76
	v_lshl_add_u64 v[40:41], v[40:41], 1, s[22:23]
	flat_store_short_d16_hi v[40:41], v25
	v_bfe_u32 v25, v31, 16, 1
	v_or_b32_e32 v40, 0x6000, v24
	v_mov_b32_e32 v41, v141
	v_add3_u32 v25, v31, v25, s76
	v_lshl_add_u64 v[40:41], v[40:41], 1, s[22:23]
	flat_store_short_d16_hi v[40:41], v25
	v_bfe_u32 v25, v27, 16, 1
	v_add3_u32 v33, v27, v25, s76
	v_or_b32_e32 v24, 0xe000, v24
	v_mov_b32_e32 v25, v141
	v_lshl_add_u64 v[24:25], v[24:25], 1, s[22:23]
	s_mov_b64 s[12:13], 0
	flat_store_short_d16_hi v[24:25], v33

; DI unsigned f2bf(float f) { unsigned u = __builtin_bit_cast(unsigned, f); return (u + 0x7fffu + ((u >> 16) & 1u)) >> 16; }
; DI unsigned pk2(float lo, float hi) { typedef float v2f __attribute__((ext_vector_type(2))); typedef __bf16 v2b __attribute__((ext_vector_type(2))); v2f v = {lo, hi}; v2b b = __builtin_convertvector(v, v2b); return __builtin_bit_cast(unsigned, b); }
;     DI void operator()(const f32x4 (&acc)[2][2][4][2], const Unit& u, int wr, int wc, int fr, int fq) const {
;     ...
;                 const int row = row0 + ai * 128 + m * 16; const float rs = row_rstd<1>(P, row, 1.0f / 256.0f);
;                 const int b = row >> 13, s = row & 8191;
; #pragma unroll
;                 for (int bj = 0; bj < 2; ++bj) {
;                     const int h = u.pn * 2 + bj;
;                     const f32x4 a = acc[ai][bj][m][0] * rs, c = acc[ai][bj][m][1] * rs;
;                     if (wc < 2) {
;                         u32x4 w; w.x = pk2(a[0], a[1]); w.y = pk2(a[2], a[3]); w.z = pk2(c[0], c[1]); w.w = pk2(c[2], c[3]);
;                         *(u32x4*)(KN + (size_t)row * 512 + h * 64 + wc * 32 + 8 * fq) = w;
;                     } else {
;                         const unsigned vo = (unsigned)((b * 8 + h) * 64 + (wc - 2) * 32 + 8 * fq) * (unsigned)SEQ + (unsigned)s;
; #pragma unroll
;                         for (int i = 0; i < 4; ++i) { Vt[vo + (unsigned)(i * SEQ)] = (bf16_t)f2bf(a[i]); Vt[vo + (unsigned)((4 + i) * SEQ)] = (bf16_t)f2bf(c[i]); }
.LBB0_1289:
	s_nop 0
	v_add_u32_e32 v18, 0xb0, v152
	s_and_b64 vcc, exec, s[4:5]
	v_and_or_b32 v22, v18, s79, v163
	s_mov_b64 s[12:13], -1
	s_waitcnt lgkmcnt(0)
	v_fmamk_f32 v16, v205, 0x3b800000, v167
	v_rsq_f32_e32 v16, v16
	s_nop 0
	v_pk_mul_f32 v[14:15], v[14:15], v[16:17] op_sel_hi:[1,0]
	v_pk_mul_f32 v[12:13], v[12:13], v[16:17] op_sel_hi:[1,0]
	v_pk_mul_f32 v[10:11], v[10:11], v[16:17] op_sel_hi:[1,0]
	v_pk_mul_f32 v[20:21], v[8:9], v[16:17] op_sel_hi:[1,0]
	s_cbranch_vccnz .LBB0_1291
	v_bfe_u32 v9, v12, 16, 1
	v_lshl_add_u32 v8, v70, 19, v22
	v_add3_u32 v17, v12, v9, s76
	v_mov_b32_e32 v9, v141
	v_lshl_add_u64 v[24:25], v[8:9], 1, s[22:23]
	flat_store_short_d16_hi v[24:25], v17
	v_bfe_u32 v9, v20, 16, 1
	v_or_b32_e32 v24, 0x8000, v8
	v_mov_b32_e32 v25, v141
	v_add3_u32 v9, v20, v9, s76
	v_lshl_add_u64 v[24:25], v[24:25], 1, s[22:23]
	flat_store_short_d16_hi v[24:25], v9
	v_bfe_u32 v9, v13, 16, 1
	v_or_b32_e32 v24, 0x2000, v8
	v_mov_b32_e32 v25, v141
	v_add3_u32 v9, v13, v9, s76
	v_lshl_add_u64 v[24:25], v[24:25], 1, s[22:23]
	flat_store_short_d16_hi v[24:25], v9
	v_bfe_u32 v9, v21, 16, 1
	v_or_b32_e32 v24, 0xa000, v8
	v_mov_b32_e32 v25, v141
	v_add3_u32 v9, v21, v9, s76
	v_lshl_add_u64 v[24:25], v[24:25], 1, s[22:23]
	flat_store_short_d16_hi v[24:25], v9
	v_bfe_u32 v9, v14, 16, 1
	v_or_b32_e32 v24, 0x4000, v8
	v_mov_b32_e32 v25, v141
	v_add3_u32 v9, v14, v9, s76
	v_lshl_add_u64 v[24:25], v[24:25], 1, s[22:23]
	flat_store_short_d16_hi v[24:25], v9
	v_bfe_u32 v9, v10, 16, 1
	v_or_b32_e32 v24, 0xc000, v8
	v_mov_b32_e32 v25, v141
	v_add3_u32 v9, v10, v9, s76
	v_lshl_add_u64 v[24:25], v[24:25], 1, s[22:23]
	flat_store_short_d16_hi v[24:25], v9
	v_bfe_u32 v9, v15, 16, 1
	v_or_b32_e32 v24, 0x6000, v8
	v_mov_b32_e32 v25, v141
	v_add3_u32 v9, v15, v9, s76
	v_lshl_add_u64 v[24:25], v[24:25], 1, s[22:23]
	flat_store_short_d16_hi v[24:25], v9
	v_bfe_u32 v9, v11, 16, 1
	v_add3_u32 v17, v11, v9, s76
	v_or_b32_e32 v8, 0xe000, v8
	v_mov_b32_e32 v9, v141
	v_lshl_add_u64 v[8:9], v[8:9], 1, s[22:23]
	s_mov_b64 s[12:13], 0
	flat_store_short_d16_hi v[8:9], v17
